# grid barrier: the 16 arrival-counter poll loads issued back to back instead of one round trip each (on top of v25)
# speedup vs baseline: 1.0270x; 1.0021x over previous
; __device__ __forceinline__ unsigned xb_ld(unsigned* p)              { return __hip_atomic_load(p, __ATOMIC_RELAXED, __HIP_MEMORY_SCOPE_AGENT); }
; __device__ __forceinline__ void xcd_barrier_complete(unsigned* bar, unsigned x, unsigned& nloc, unsigned& nx) {
;     const unsigned G = gridDim.x * gridDim.y * gridDim.z;
;     unsigned sum, cnt, mine, sp = 0u;
;     for (;;) {
;         sum = 0u; cnt = 0u; mine = 0u;
; #pragma unroll
;         for (unsigned j = 0; j < 16; ++j) { const unsigned c = xb_ld(&bar[XB_XCNT(j)]); sum += c; cnt += (c > 0u) ? 1u : 0u; mine = (j == x) ? c : mine; }
;         if (sum == G) break;
;         __builtin_amdgcn_s_sleep(1);
;         if ((++sp & 255u) == 0u) { if (xb_ld(&bar[XB_TMO])) break; if (sp > XB_SPIN_CAP) { atomicAdd(&bar[XB_TMO], 1u); break; } }
;     }
;     nloc = mine > 0u ? mine : 1u; nx = cnt > 0u ? cnt : 1u;
; }
.LBB0_104:
	v_readlane_b32 s10, v251, 28
	v_readlane_b32 s11, v251, 29
	s_waitcnt lgkmcnt(0)
	global_load_dword v2, v1, s[76:77] sc1
	global_load_dword v0, v1, s[78:79] sc1
	s_mov_b64 s[18:19], -1
	s_nop 1
	global_load_dword v3, v1, s[10:11] sc1
	v_readlane_b32 s10, v251, 30
	v_readlane_b32 s11, v251, 31
	s_nop 4
	global_load_dword v4, v1, s[10:11] sc1
	v_readlane_b32 s10, v251, 32
	v_readlane_b32 s11, v251, 33
	s_nop 4
	global_load_dword v5, v1, s[10:11] sc1
	v_readlane_b32 s10, v251, 34
	v_readlane_b32 s11, v251, 35
	s_nop 4
	global_load_dword v6, v1, s[10:11] sc1
	v_readlane_b32 s10, v251, 36
	v_readlane_b32 s11, v251, 37
	s_nop 4
	global_load_dword v7, v1, s[10:11] sc1
	v_readlane_b32 s10, v251, 38
	v_readlane_b32 s11, v251, 39
	s_nop 4
	global_load_dword v8, v1, s[10:11] sc1
	v_readlane_b32 s10, v251, 40
	v_readlane_b32 s11, v251, 41
	s_nop 4
	global_load_dword v9, v1, s[10:11] sc1
	v_readlane_b32 s10, v251, 42
	v_readlane_b32 s11, v251, 43
	s_nop 4
	global_load_dword v10, v1, s[10:11] sc1
	v_readlane_b32 s10, v251, 44
	v_readlane_b32 s11, v251, 45
	s_nop 4
	global_load_dword v11, v1, s[10:11] sc1
	v_readlane_b32 s10, v251, 46
	v_readlane_b32 s11, v251, 47
	s_nop 4
	global_load_dword v12, v1, s[10:11] sc1
	global_load_dword v13, v1, s[58:59] sc1
	global_load_dword v14, v1, s[0:1] sc1
	global_load_dword v15, v1, s[94:95] sc1
	global_load_dword v16, v1, s[96:97] sc1
	s_mov_b64 s[10:11], -1
	s_waitcnt vmcnt(14)
	v_add_u32_e32 v17, v0, v2
	s_waitcnt vmcnt(13)
	v_add_u32_e32 v17, v17, v3
	s_waitcnt vmcnt(12)
	v_add_u32_e32 v17, v17, v4
	s_waitcnt vmcnt(11)
	v_add_u32_e32 v17, v17, v5
	s_waitcnt vmcnt(10)
	v_add_u32_e32 v17, v17, v6
	s_waitcnt vmcnt(9)
	v_add_u32_e32 v17, v17, v7
	s_waitcnt vmcnt(8)
	v_add_u32_e32 v17, v17, v8
	s_waitcnt vmcnt(7)
	v_add_u32_e32 v17, v17, v9
	s_waitcnt vmcnt(6)
	v_add_u32_e32 v17, v17, v10
	s_waitcnt vmcnt(5)
	v_add_u32_e32 v17, v17, v11
	s_waitcnt vmcnt(4)
	v_add_u32_e32 v17, v17, v12
	s_waitcnt vmcnt(3)
	v_add_u32_e32 v17, v17, v13
	s_waitcnt vmcnt(2)
	v_add_u32_e32 v17, v17, v14
	s_waitcnt vmcnt(1)
	v_add_u32_e32 v17, v17, v15
	s_waitcnt vmcnt(0)
	v_add_u32_e32 v17, v17, v16
	v_cmp_eq_u32_e32 vcc, s55, v17
	s_cbranch_vccnz .LBB0_103
	s_and_b32 s10, s28, 0xff
	s_cmp_eq_u32 s10, 0
	s_mov_b64 s[10:11], -1
	s_mov_b64 s[20:21], -1
	s_sleep 1
	s_cbranch_scc0 .LBB0_108
	global_load_dword v17, v1, s[74:75] sc1
	s_waitcnt vmcnt(0)
	v_cmp_eq_u32_e32 vcc, 0, v17
	s_cbranch_vccnz .LBB0_110
	s_mov_b64 s[20:21], 0
